# FoX item prologue: first K/V tile, forget-gate slice, forget bias and gain vectors requested together with the Q rows
# speedup vs baseline: 1.0040x; 1.0026x over previous
; #define LAS __attribute__((address_space(3)))
; __device__ __forceinline__ unsigned pk2(float lo, float hi) { f32x2 v = {lo, hi}; bf16x2_t b = __builtin_convertvector(v, bf16x2_t); return __builtin_bit_cast(unsigned, b); }
; __device__ __forceinline__ float bflo(unsigned u) { return __uint_as_float(u << 16); }
; template <int MODE>
; __device__ __forceinline__ void attn_item(const AttnP& p, int b, int h, int qb, LAS unsigned char* lds) {
;     ...
;     const int tok0 = b * SEQ, q0 = qb * 256, qw = q0 + 32 * w, qrow = qw + ln;
;     const bf16_t* P = p.P;
;     bf16x8 Qf[NC][4];
; #pragma unroll
;     for (int c = 0; c < NC; ++c) {
;         u32x4 raw[4]; float ss = 0.f;
; #pragma unroll
;         for (int ks = 0; ks < 4; ++ks) {
;             raw[ks] = *(const u32x4*)(P + (size_t)(tok0 + qrow) * PP + qcol + c * 64 + ks * 16 + hh * 8);
; #pragma unroll
;             for (int e = 0; e < 4; ++e) { const float lo = bflo(raw[ks][e]), hi = bfhi(raw[ks][e]); ss += lo * lo + hi * hi; }
;         }
;         float sc = 0.125f * LOG2E;
;         if (MODE != 1) { ss += __shfl_xor(ss, 32); sc *= 1.0f / sqrtf(ss * (1.0f / 64.0f) + 1e-6f); }
; #pragma unroll
;         for (int ks = 0; ks < 4; ++ks) {
;             u32x4 o;
; #pragma unroll
;             for (int e = 0; e < 4; ++e) {
;                 float lo = bflo(raw[ks][e]) * sc, hi = bfhi(raw[ks][e]) * sc;
;                 if (MODE != 1) {
;                     const int d = ks * 16 + hh * 8 + 2 * e;
;                     const float* gq = p.qk_gain + ((MODE == 0) ? 0 : 128); const float* gk = gq + 64;
;                     lo *= gq[d] * gk[d]; hi *= gq[d + 1] * gk[d + 1];
;                 }
;                 o[e] = pk2(lo, hi);
;             }
;             Qf[c][ks] = __builtin_bit_cast(bf16x8, o);
;             if (QPARK) *(LAS u32x4*)(lds + QP_OFF + w * 8192 + ((c * 4 + ks) * 64 + lane) * 16) = o;
;     ...
;         float gq_ = fabsf(p.qk_gain[128 + lane]), gk_ = fabsf(p.qk_gain[192 + lane]);
; #pragma unroll
;         for (int o_ = 1; o_ < 64; o_ <<= 1) { gq_ = fmaxf(gq_, __shfl_xor(gq_, o_)); gk_ = fmaxf(gk_, __shfl_xor(gk_, o_)); }
;         qk2 = 8.0f * gq_ * gk_ * LOG2E * 1.02f;
;     }
;     const float fb = (MODE == 2) ? p.fbias[h] : 0.f;
;     const int jt_max = qb * 4 + 3;
;     u32x4 kreg[NC], vreg[NC]; float cfreg = 0.f;
.LBB0_213:
	s_or_b64 exec, exec, s[0:1]
	v_readlane_b32 s0, v254, 19
	s_waitcnt lgkmcnt(0)
	s_barrier
	v_mov_b32_e32 v0, s0
	ds_read_b32 v0, v0
	s_movk_i32 s0, 0x4ff
	s_waitcnt lgkmcnt(0)
	v_cmp_lt_i32_e32 vcc, s0, v0
	v_readfirstlane_b32 s3, v0
	s_mov_b64 s[0:1], -1
	s_cbranch_vccnz .LBB0_210
	s_cmpk_gt_i32 s3, 0xff
	v_writelane_b32 v252, s3, 9
	s_cbranch_scc0 .LBB0_243
	s_add_i32 s0, s3, 0xffffff00
	v_mov_b32_e32 v123, v210
	s_lshr_b32 s22, s0, 6
	s_sub_i32 s2, 15, s22
	v_readfirstlane_b32 s5, v123
	s_lshl_b32 s0, s3, 9
	s_ashr_i32 s1, s5, 1
	s_and_b32 s26, s0, 0x7000
	s_lshl_b32 s0, s2, 8
	s_and_b32 s27, s1, 0xffffffe0
	v_and_b32_e32 v122, 31, v123
	s_add_i32 s27, s27, s0
	v_or_b32_e32 v115, s27, v122
	s_and_b32 s4, s3, 7
	v_add_u32_e32 v0, s26, v115
	s_waitcnt vmcnt(0)
	v_mov_b64_e32 v[2:3], s[68:69]
	v_bfe_u32 v124, v123, 5, 1
	v_mad_i64_i32 v[2:3], s[0:1], v0, s76, v[2:3]
	s_lshl_b32 s92, s4, 7
	v_lshl_add_u64 v[2:3], v[2:3], 0, s[92:93]
	v_lshlrev_b32_e32 v88, 4, v124
	v_mov_b32_e32 v89, v1
	v_lshl_add_u64 v[2:3], v[2:3], 0, v[88:89]
	global_load_dwordx4 v[64:67], v[2:3], off offset:96
	global_load_dwordx4 v[68:71], v[2:3], off offset:64
	global_load_dwordx4 v[100:103], v[2:3], off offset:32
	global_load_dwordx4 v[116:119], v[2:3], off
	s_lshl_b32 s100, s2, 2
	s_or_b32 s100, s100, 3
	s_lshl_b32 s100, s100, 6
	s_or_b32 s100, s100, s26
	v_ashrrev_i32_e32 v156, 3, v123
	v_add_u32_e32 v156, s100, v156
	v_mov_b64_e32 v[154:155], s[68:69]
	v_mad_i64_i32 v[154:155], vcc, v156, s76, v[154:155]
	v_lshlrev_b32_e32 v156, 3, v123
	v_and_b32_e32 v156, 56, v156
	v_lshlrev_b32_e32 v156, 1, v156
	v_mov_b32_e32 v157, 0
	v_lshl_add_u64 v[154:155], v[154:155], 0, v[156:157]
	v_lshl_add_u64 v[154:155], v[154:155], 0, s[92:93]
	global_load_dwordx4 v[142:145], v[154:155], off offset:1024
	global_load_dwordx4 v[146:149], v[154:155], off offset:2048
	v_mov_b32_e32 v150, 0
	s_cmp_gt_u32 s5, 63
	s_cbranch_scc1 .Lfp_nocf
	v_and_b32_e32 v156, 63, v123
	v_or_b32_e32 v156, s100, v156
	v_mul_u32_u24_e32 v156, 0x50, v156
	v_or_b32_e32 v156, s4, v156
	v_lshl_add_u32 v156, v156, 2, v217
	global_load_dword v150, v156, s[84:85]
.Lfp_nocf:
	v_readlane_b32 s100, v254, 61
	v_readlane_b32 s101, v254, 62
	v_and_b32_e32 v156, 63, v123
	v_lshlrev_b32_e32 v156, 2, v156
	global_load_dword v152, v156, s[90:91] offset:512
	global_load_dword v153, v156, s[90:91] offset:768
	v_mov_b32_e32 v157, s4
	v_lshlrev_b32_e32 v157, 2, v157
	s_nop 1
	global_load_dword v151, v157, s[100:101]
	v_and_b32_e32 v0, 64, v216
	v_xor_b32_e32 v2, 32, v216
	v_add_u32_e32 v0, 64, v0
	v_cmp_lt_i32_e32 vcc, v2, v0
	v_and_b32_e32 v22, 32, v123
	v_cndmask_b32_e32 v2, v216, v2, vcc
	v_lshlrev_b32_e32 v114, 2, v2
	global_load_dwordx4 v[2:5], v22, s[90:91] offset:720
	global_load_dwordx4 v[26:29], v22, s[90:91] offset:704
	global_load_dwordx4 v[6:9], v22, s[90:91] offset:976
	global_load_dwordx4 v[34:37], v22, s[90:91] offset:960
	global_load_dwordx4 v[38:41], v22, s[90:91] offset:656
	global_load_dwordx4 v[30:33], v22, s[90:91] offset:640
	global_load_dwordx4 v[46:49], v22, s[90:91] offset:912
	global_load_dwordx4 v[42:45], v22, s[90:91] offset:896
	global_load_dwordx4 v[58:61], v22, s[90:91] offset:592
	global_load_dwordx4 v[10:13], v22, s[90:91] offset:576
	global_load_dwordx4 v[72:75], v22, s[90:91] offset:848
	global_load_dwordx4 v[14:17], v22, s[90:91] offset:832
	global_load_dwordx4 v[50:53], v22, s[90:91] offset:528
	global_load_dwordx4 v[18:21], v22, s[90:91] offset:512
	global_load_dwordx4 v[54:57], v22, s[90:91] offset:784
	s_nop 0
	global_load_dwordx4 v[22:25], v22, s[90:91] offset:768
	s_waitcnt vmcnt(0) lgkmcnt(0)
	v_and_b32_e32 v85, 0xffff0000, v65
	v_and_b32_e32 v83, 0xffff0000, v71
	v_and_b32_e32 v87, 0xffff0000, v67
	v_lshlrev_b32_e32 v84, 16, v64
	v_and_b32_e32 v111, 0xffff0000, v64
	v_lshlrev_b32_e32 v82, 16, v70
	v_and_b32_e32 v109, 0xffff0000, v70
	v_mov_b32_e32 v110, v85
	v_mov_b32_e32 v108, v83
	v_lshlrev_b32_e32 v86, 16, v66
	v_and_b32_e32 v113, 0xffff0000, v66
	v_lshlrev_b32_e32 v90, 16, v65
	v_lshlrev_b32_e32 v92, 16, v71
	v_mov_b32_e32 v112, v87
	v_mov_b32_e32 v91, v84
	v_mov_b32_e32 v93, v82
	v_pk_mul_f32 v[104:105], v[110:111], v[110:111]
	v_pk_mul_f32 v[106:107], v[108:109], v[108:109]
	v_lshlrev_b32_e32 v62, 16, v67
	v_lshlrev_b32_e32 v96, 16, v103
	v_and_b32_e32 v97, 0xffff0000, v103
	v_lshlrev_b32_e32 v78, 16, v102
	v_and_b32_e32 v79, 0xffff0000, v102
	v_mov_b32_e32 v63, v86
	v_pk_mul_f32 v[102:103], v[112:113], v[112:113]
	v_pk_fma_f32 v[130:131], v[90:91], v[90:91], v[104:105]
	v_pk_fma_f32 v[132:133], v[92:93], v[92:93], v[106:107]
	v_lshlrev_b32_e32 v104, 16, v117
	v_and_b32_e32 v105, 0xffff0000, v117
	v_lshlrev_b32_e32 v106, 16, v116
	v_and_b32_e32 v107, 0xffff0000, v116
	v_pk_fma_f32 v[128:129], v[62:63], v[62:63], v[102:103]
	v_lshlrev_b32_e32 v102, 16, v118
	v_and_b32_e32 v103, 0xffff0000, v118
	v_pk_mul_f32 v[136:137], v[104:105], v[104:105]
	v_pk_mul_f32 v[116:117], v[106:107], v[106:107]
	v_lshlrev_b32_e32 v98, 16, v101
	v_and_b32_e32 v99, 0xffff0000, v101
	v_lshlrev_b32_e32 v76, 16, v100
	v_and_b32_e32 v77, 0xffff0000, v100
	v_lshlrev_b32_e32 v100, 16, v119
	v_and_b32_e32 v101, 0xffff0000, v119
	v_pk_mul_f32 v[118:119], v[102:103], v[102:103]
	v_add_f32_e32 v89, v136, v137
	v_add_f32_e32 v91, v116, v117
	v_pk_mul_f32 v[134:135], v[100:101], v[100:101]
	v_add_f32_e32 v89, v91, v89
	v_add_f32_e32 v91, v118, v119
	v_pk_mul_f32 v[126:127], v[76:77], v[76:77]
	v_add_f32_e32 v63, v134, v135
	v_add_f32_e32 v89, v91, v89
	v_pk_mul_f32 v[120:121], v[98:99], v[98:99]
	v_add_f32_e32 v63, v63, v89
	v_add_f32_e32 v89, v126, v127
	v_pk_mul_f32 v[70:71], v[78:79], v[78:79]
; __device__ __forceinline__ float bflo(unsigned u) { return __uint_as_float(u << 16); }
; __device__ __forceinline__ float bfhi(unsigned u) { return __uint_as_float(u & 0xffff0000u); }
; template <int MODE>
; __device__ __forceinline__ void attn_item(const AttnP& p, int b, int h, int qb, LAS unsigned char* lds) {
;     ...
;             for (int e = 0; e < 4; ++e) { const float lo = bflo(raw[ks][e]), hi = bfhi(raw[ks][e]); ss += lo * lo + hi * hi; }
;         }
;         float sc = 0.125f * LOG2E;
;         if (MODE != 1) { ss += __shfl_xor(ss, 32); sc *= 1.0f / sqrtf(ss * (1.0f / 64.0f) + 1e-6f); }
;     ...
;         float gq_ = fabsf(p.qk_gain[128 + lane]), gk_ = fabsf(p.qk_gain[192 + lane]);
; #pragma unroll
;         for (int o_ = 1; o_ < 64; o_ <<= 1) { gq_ = fmaxf(gq_, __shfl_xor(gq_, o_)); gk_ = fmaxf(gk_, __shfl_xor(gk_, o_)); }
;         qk2 = 8.0f * gq_ * gk_ * LOG2E * 1.02f;
;     }
;     const float fb = (MODE == 2) ? p.fbias[h] : 0.f;
;     const int jt_max = qb * 4 + 3;
;     u32x4 kreg[NC], vreg[NC]; float cfreg = 0.f;
	v_add_f32_e32 v63, v89, v63
	v_add_f32_e32 v89, v120, v121
	v_lshlrev_b32_e32 v94, 16, v69
	v_and_b32_e32 v95, 0xffff0000, v69
	v_lshlrev_b32_e32 v80, 16, v68
	v_and_b32_e32 v81, 0xffff0000, v68
	v_pk_mul_f32 v[68:69], v[96:97], v[96:97]
	v_add_f32_e32 v63, v89, v63
	v_add_f32_e32 v70, v70, v71
	v_pk_mul_f32 v[66:67], v[80:81], v[80:81]
	v_add_f32_e32 v63, v70, v63
	v_add_f32_e32 v68, v68, v69
	v_pk_mul_f32 v[64:65], v[94:95], v[94:95]
	v_add_f32_e32 v63, v68, v63
	v_add_f32_e32 v66, v66, v67
	v_add_f32_e32 v63, v66, v63
	v_add_f32_e32 v64, v64, v65
	v_add_f32_e32 v63, v64, v63
	v_add_f32_e32 v63, v133, v63
	v_add_f32_e32 v63, v132, v63
	v_add_f32_e32 v63, v131, v63
	v_add_f32_e32 v63, v130, v63
	v_add_f32_e32 v63, v129, v63
	v_add_f32_e32 v125, v128, v63
	ds_bpermute_b32 v126, v114, v125
	v_cmp_gt_i32_e32 vcc, 4, v123
	s_and_saveexec_b64 s[0:1], vcc
	v_lshl_add_u32 v63, v123, 2, 0
	ds_write_b32 v63, v1 offset:44672
	s_or_b64 exec, exec, s[0:1]
	v_and_b32_e32 v89, 63, v123
	v_lshlrev_b32_e32 v63, 2, v89
	v_mov_b32_e32 v64, v152
	v_xor_b32_e32 v67, 1, v216
	v_mov_b32_e32 v63, v153
	v_cmp_lt_i32_e32 vcc, v67, v0
	s_lshl_b32 s18, s4, 2
	v_readlane_b32 s0, v254, 61
	v_cndmask_b32_e32 v67, v216, v67, vcc
	v_lshlrev_b32_e32 v67, 2, v67
	s_lshl_b32 s28, s2, 2
	v_readlane_b32 s1, v254, 62
	s_or_b32 s29, s28, 3
	v_ashrrev_i32_e32 v127, 3, v123
	s_lshl_b32 s20, s4, 6
	s_lshl_b32 s92, s20, 1
	v_mov_b32_e32 v112, 0
	v_and_b32_e32 v65, 0x7fffffff, v64
	ds_bpermute_b32 v65, v67, v65
	v_and_b32_e32 v66, 0x7fffffff, v63
	v_max_f32_e64 v64, |v64|, |v64|
	v_max_f32_e64 v63, |v63|, |v63|
	s_waitcnt lgkmcnt(0)
	v_max_f32_e32 v65, v65, v65
	v_max_f32_e32 v64, v64, v65
	ds_bpermute_b32 v65, v67, v66
	s_waitcnt lgkmcnt(0)
	v_max_f32_e32 v65, v65, v65
	v_max_f32_e32 v63, v63, v65
	v_xor_b32_e32 v65, 2, v216
	v_cmp_lt_i32_e32 vcc, v65, v0
	s_nop 1
	v_cndmask_b32_e32 v65, v216, v65, vcc
	v_lshlrev_b32_e32 v65, 2, v65
	ds_bpermute_b32 v66, v65, v64
	ds_bpermute_b32 v65, v65, v63
	s_waitcnt lgkmcnt(1)
	v_max_f32_e32 v66, v66, v66
	s_waitcnt lgkmcnt(0)
	v_max_f32_e32 v65, v65, v65
	v_max_f32_e32 v63, v63, v65
	v_xor_b32_e32 v65, 4, v216
	v_cmp_lt_i32_e32 vcc, v65, v0
	v_max_f32_e32 v64, v64, v66
	s_nop 0
	v_cndmask_b32_e32 v65, v216, v65, vcc
	v_lshlrev_b32_e32 v65, 2, v65
	ds_bpermute_b32 v66, v65, v64
	ds_bpermute_b32 v65, v65, v63
	s_waitcnt lgkmcnt(1)
	v_max_f32_e32 v66, v66, v66
	s_waitcnt lgkmcnt(0)
	v_max_f32_e32 v65, v65, v65
	v_max_f32_e32 v63, v63, v65
	v_xor_b32_e32 v65, 8, v216
	v_cmp_lt_i32_e32 vcc, v65, v0
	v_max_f32_e32 v64, v64, v66
	s_nop 0
	v_cndmask_b32_e32 v65, v216, v65, vcc
	v_lshlrev_b32_e32 v65, 2, v65
	ds_bpermute_b32 v66, v65, v64
	ds_bpermute_b32 v65, v65, v63
	s_waitcnt lgkmcnt(1)
	v_max_f32_e32 v66, v66, v66
	s_waitcnt lgkmcnt(0)
	v_max_f32_e32 v65, v65, v65
	v_max_f32_e32 v65, v63, v65
	v_xor_b32_e32 v63, 16, v216
	v_cmp_lt_i32_e32 vcc, v63, v0
	v_max_f32_e32 v64, v64, v66
	s_nop 0
	v_cndmask_b32_e32 v0, v216, v63, vcc
	v_lshlrev_b32_e32 v0, 2, v0
	ds_bpermute_b32 v63, v0, v64
	ds_bpermute_b32 v0, v0, v65
	s_waitcnt lgkmcnt(1)
	v_max_f32_e32 v63, v63, v63
	s_waitcnt lgkmcnt(0)
	v_max_f32_e32 v0, v0, v0
	v_max_f32_e32 v91, v65, v0
	v_mov_b32_e32 v0, s18
	v_mov_b32_e32 v110, v151
	s_lshl_b32 s0, s29, 6
	s_or_b32 s6, s0, s26
	v_max_f32_e32 v63, v64, v63
	v_add_u32_e32 v0, s6, v127
	v_mov_b64_e32 v[64:65], s[68:69]
	v_mad_i64_i32 v[64:65], s[0:1], v0, s76, v[64:65]
	v_lshlrev_b32_e32 v0, 3, v123
	v_and_b32_e32 v108, 56, v0
	v_lshlrev_b32_e32 v0, 1, v108
	v_lshl_add_u64 v[64:65], v[64:65], 0, v[0:1]
	v_lshl_add_u64 v[68:69], v[64:65], 0, s[92:93]
	v_mov_b64_e32 v[64:65], v[142:143]
	v_mov_b64_e32 v[66:67], v[144:145]
	ds_bpermute_b32 v121, v114, v63
	ds_bpermute_b32 v93, v114, v91
	s_cmp_lt_u32 s5, 64
	s_cselect_b64 s[2:3], -1, 0
	s_cmp_gt_u32 s5, 63
	s_cselect_b64 s[0:1], -1, 0
	s_and_b64 vcc, exec, s[0:1]
	s_cbranch_vccnz .LBB0_219
	v_or_b32_e32 v70, s6, v89
	v_mul_u32_u24_e32 v70, 0x50, v70
	v_or_b32_e32 v70, s4, v70
	v_lshl_add_u32 v70, v70, 2, v217
	v_mov_b32_e32 v71, v1
	v_lshl_add_u64 v[70:71], s[84:85], 0, v[70:71]
	v_mov_b32_e32 v112, v150
.LBB0_219:
	s_nop 0
	v_mov_b64_e32 v[68:69], v[146:147]
	v_mov_b64_e32 v[70:71], v[148:149]
	s_waitcnt vmcnt(0) lgkmcnt(0)
	v_and_b32_e32 v119, 0xffff0000, v67
	v_and_b32_e32 v131, 0xffff0000, v66
	v_lshlrev_b32_e32 v118, 16, v67
	v_lshlrev_b32_e32 v130, 16, v66
	v_mov_b32_e32 v132, v119
	v_mov_b32_e32 v133, v131
	v_mov_b32_e32 v128, v118
	v_mov_b32_e32 v129, v130
	v_pk_mul_f32 v[132:133], v[132:133], v[132:133]
	v_and_b32_e32 v135, 0xffff0000, v64
	v_pk_fma_f32 v[128:129], v[128:129], v[128:129], v[132:133]
	v_and_b32_e32 v133, 0xffff0000, v65
	v_lshlrev_b32_e32 v132, 16, v65
	v_lshlrev_b32_e32 v134, 16, v64
	v_mov_b32_e32 v138, v135
	v_mov_b32_e32 v139, v133
	v_mov_b32_e32 v136, v134
	v_mov_b32_e32 v137, v132
	v_pk_mul_f32 v[138:139], v[138:139], v[138:139]
	v_mad_u64_u32 v[116:117], s[4:5], v127, s72, v[108:109]
	v_pk_fma_f32 v[136:137], v[136:137], v[136:137], v[138:139]
	v_lshlrev_b32_e32 v108, 1, v116
	v_add_f32_e32 v120, v136, v137
	v_add_f32_e32 v120, v129, v120
	v_add_f32_e32 v120, v128, v120
	v_mul_lo_u32 v117, v127, 24
	v_add_lshl_u32 v116, v116, v117, 1
	v_add_f32_dpp v120, v120, v120 quad_perm:[1,0,3,2] row_mask:0xf bank_mask:0xf bound_ctrl:1
	v_add_u32_e32 v117, 0, v108
	s_mov_b64 s[4:5], -1
	v_add_f32_dpp v120, v120, v120 quad_perm:[2,3,0,1] row_mask:0xf bank_mask:0xf bound_ctrl:1
	s_andn2_b64 vcc, exec, s[0:1]
	s_nop 0
	v_add_f32_dpp v120, v120, v120 row_half_mirror row_mask:0xf bank_mask:0xf bound_ctrl:1
	v_fmamk_f32 v120, v120, 0x3c800000, v211
	v_rsq_f32_e32 v120, v120
	s_nop 0
	v_pk_mul_f32 v[128:129], v[120:121], v[134:135] op_sel_hi:[0,1]
	v_pk_mul_f32 v[132:133], v[120:121], v[132:133] op_sel_hi:[0,1]
	v_pk_mul_f32 v[130:131], v[120:121], v[130:131] op_sel_hi:[0,1]
	v_pk_mul_f32 v[118:119], v[120:121], v[118:119] op_sel_hi:[0,1]
	v_cvt_pk_bf16_f32 v128, v128, v129
	v_cvt_pk_bf16_f32 v129, v132, v133
	v_cvt_pk_bf16_f32 v130, v130, v131
	v_cvt_pk_bf16_f32 v131, v118, v119
	v_add_u32_e32 v118, 0, v116
	ds_write_b128 v117, v[128:131]
	ds_write_b128 v118, v[68:71] offset:9216
	v_lshlrev_b32_e32 v117, 2, v216
	v_and_b32_e32 v128, 63, v216
	v_or_b32_e32 v129, 0x80, v117
	v_and_b32_e32 v131, 0x100, v117
	s_cbranch_vccnz .LBB0_221
	v_and_b32_e32 v130, 63, v216
	v_or_b32_e32 v118, 0x80, v117
	v_and_b32_e32 v119, 0x100, v117
	s_mov_b64 s[4:5], 0
